# adds early work-queue fetch in the NSA unit and LDS-staged page table in the decode-row NSA unit
# speedup vs baseline: 1.0078x; 1.0033x over previous
; #define LAS __attribute__((address_space(3)))
; DI void snsa_unit(const Args& a, LAS unsigned char* lds, int s, int g) {
;     ...
;     const int tid = tid_, lane = tid & 63, wave = __builtin_amdgcn_readfirstlane(tid >> 6), ksl = tid >> 4, c16 = tid & 15;
;     const size_t row = (size_t)MPR + s;
;     LAS float* SC = (LAS float*)(lds + S_SC); LAS unsigned long long* VP = (LAS unsigned long long*)(lds + S_VP); LAS float* Q = (LAS float*)(lds + S_Q); LAS float* RED = (LAS float*)(lds + S_RED);
;     LAS float* OBR = (LAS float*)(lds + S_OB); LAS float* IMP = (LAS float*)(lds + S_IMP); LAS int* SEL = (LAS int*)(lds + S_SEL);
;     const float* rbias = INF(a, I_RB); const int* pt = (const int*)a.in[I_PT] + s * NPAGES;
;     const bf16_t* kcb = (const bf16_t*)(ws + WS_KC) + ((size_t)AROWS_P + (size_t)(s * 2 + g) * 1024) * 64; const bf16_t* vcb = kcb + (size_t)AROWS * 64;
;     __syncthreads();
;     if (tid < 256) Q[tid] = bf2f(((const bf16_t*)(ws + WS_QA))[row * 512 + g * 256 + tid]);
;     __syncthreads();
;     f32x4 q4[4];
; #pragma unroll
;     for (int hq = 0; hq < 4; ++hq) q4[hq] = *(const LAS f32x4*)(Q + hq * 64 + 4 * c16);
;     const int myh = 2 * (c16 & 1) + ((c16 >> 1) & 1);
.LBB0_1458:
	s_or_b64 exec, exec, s[6:7]
	s_lshl_b32 s6, s4, 7
	s_ashr_i32 s7, s6, 31
	v_readlane_b32 s8, v253, 36
	s_lshl_b64 s[6:7], s[6:7], 2
	v_readlane_b32 s10, v253, 38
	v_readlane_b32 s11, v253, 39
	s_add_u32 s74, s10, s6
	s_addc_u32 s75, s11, s7
	v_cmp_gt_u32_e32 vcc, 0x80, v72
	s_and_saveexec_b64 s[100:101], vcc
	v_lshlrev_b32_e32 v2, 2, v72
	global_load_dword v1, v2, s[74:75]
	s_waitcnt vmcnt(0)
	ds_write_b32 v2, v1 offset:62784
	s_or_b64 exec, exec, s[100:101]
	s_ashr_i32 s1, s0, 31
	s_lshl_b64 s[0:1], s[0:1], 17
	v_readlane_b32 s36, v254, 49
	v_readlane_b32 s37, v254, 50
	s_add_u32 s10, s36, s0
	s_addc_u32 s11, s37, s1
	s_cmp_lt_i32 s2, 4
	s_cselect_b64 s[6:7], -1, 0
	v_and_b32_e32 v1, 15, v72
	v_writelane_b32 v254, s6, 27
	s_movk_i32 s3, 0x101
	v_lshlrev_b32_e32 v6, 4, v1
	v_writelane_b32 v254, s7, 28
	v_cmp_gt_i32_e64 s[6:7], s3, v72
	v_readlane_b32 s12, v253, 40
	v_readlane_b32 s13, v253, 41
	v_add_u32_e32 v2, 0, v6
	v_writelane_b32 v254, s6, 29
	v_readlane_b32 s14, v253, 42
	v_readlane_b32 s15, v253, 43
	s_waitcnt lgkmcnt(0)
	s_barrier
	ds_read_b128 v[22:25], v2 offset:24576
	ds_read_b128 v[26:29], v2 offset:24832
	ds_read_b128 v[30:33], v2 offset:25088
	ds_read_b128 v[34:37], v2 offset:25344
	v_and_b32_e32 v2, 1, v72
	v_bfrev_b32_e32 v3, v72
	v_writelane_b32 v254, s7, 30
	v_cmp_eq_u32_e64 s[12:13], 0, v1
	v_lshlrev_b32_e32 v70, 3, v1
	v_lshlrev_b32_e32 v8, 2, v72
	v_lshlrev_b32_e32 v76, 2, v1
	v_cmp_ne_u32_e64 s[6:7], 0, v1
	v_writelane_b32 v254, s12, 11
	v_lshl_add_u64 v[78:79], s[10:11], 0, v[70:71]
	v_cmp_eq_u32_e64 s[10:11], 0, v2
	v_and_b32_e32 v2, 2, v72
	v_cmp_gt_u32_e64 s[14:15], 4, v1
	v_lshrrev_b32_e32 v1, 18, v3
	v_writelane_b32 v254, s13, 12
	v_cmp_eq_u32_e64 s[12:13], 0, v2
	v_and_b32_e32 v2, 0x3000, v1
	v_add_u32_e32 v1, -1, v8
	v_cmp_lt_i32_e32 vcc, 0, v72
	s_lshl_b32 s3, s24, 2
	v_writelane_b32 v252, s3, 7
	v_cndmask_b32_e32 v9, 0, v1, vcc
	v_or_b32_e32 v1, 3, v8
	s_lshl_b32 s34, s2, 12
	s_mov_b64 s[2:3], 0x840000
	v_min_i32_e32 v100, 0x3fe, v1
	v_lshl_add_u64 v[80:81], v[78:79], 0, s[2:3]
	v_cmp_le_i32_e64 s[2:3], v9, v100
	v_readlane_b32 s18, v253, 46
	v_readlane_b32 s19, v253, 47
	v_writelane_b32 v254, s2, 35
	v_cmp_eq_u32_e32 vcc, 0, v72
	v_readlane_b32 s9, v253, 37
	v_writelane_b32 v254, s3, 36
	s_movk_i32 s2, 0xfe
	v_cmp_lt_i32_e64 s[18:19], s2, v72
	s_or_b64 s[2:3], vcc, s[18:19]
	s_ashr_i32 s5, s4, 31
	v_writelane_b32 v252, s2, 8
	v_readlane_b32 s16, v253, 44
	v_readlane_b32 s17, v253, 45
	v_readlane_b32 s20, v253, 48
	v_readlane_b32 s21, v253, 49
	v_readlane_b32 s22, v253, 50
	v_readlane_b32 s23, v253, 51
	s_lshl_b64 s[8:9], s[4:5], 19
	s_lshl_b32 s76, s24, 6
	s_lshl_b64 s[4:5], s[4:5], 11
	v_writelane_b32 v252, s3, 9
	v_readlane_b32 s2, v254, 53
	s_mov_b32 s35, s24
	s_add_u32 s38, s2, s8
	v_readlane_b32 s2, v254, 54
	v_readlane_b32 s16, v253, 20
	s_addc_u32 s77, s2, s9
	v_readlane_b32 s26, v253, 30
	v_readlane_b32 s27, v253, 31
	s_add_u32 s96, s26, s8
	s_addc_u32 s97, s27, s9
	v_readlane_b32 s2, v254, 55
	s_add_u32 s2, s2, s4
	v_readlane_b32 s3, v254, 56
	s_addc_u32 s3, s3, s5
	s_lshl_b32 s4, s35, 8
	s_add_u32 s2, s2, s4
	v_ashrrev_i32_e32 v74, 4, v72
	s_addc_u32 s3, s3, 0
	s_add_u32 s62, s2, 0x400
	v_lshlrev_b32_e32 v10, 2, v74
	s_addc_u32 s63, s3, 0
	v_add3_u32 v105, v2, v10, 0
	v_and_b32_e32 v2, -16, v72
	v_ashrrev_i32_e32 v75, 31, v74
	s_add_u32 s64, s2, 0x600
	v_alignbit_b32 v104, s35, v3, 30
	s_movk_i32 s2, 0x100
	v_sub_u32_e32 v107, 0x3fe1, v2
	v_lshlrev_b64 v[2:3], 7, v[74:75]
	s_addc_u32 s65, s3, 0
	v_cmp_lt_i32_e64 s[4:5], s2, v72
	s_add_i32 s2, 0, 0x4000
	v_lshl_add_u64 v[2:3], s[0:1], 0, v[2:3]
	v_readlane_b32 s0, v254, 61
	v_writelane_b32 v252, s35, 10
	s_add_u32 s0, s0, s8
	v_readlane_b32 s1, v254, 62
	v_and_b32_e32 v73, 63, v72
	v_writelane_b32 v252, s4, 11
	v_lshlrev_b64 v[4:5], 10, v[74:75]
	s_addc_u32 s1, s1, s9
	v_writelane_b32 v252, s5, 12
	v_lshl_add_u64 v[84:85], s[0:1], 0, v[4:5]
	v_lshlrev_b32_e32 v108, 2, v73
	s_add_i32 s0, s34, 0
	v_writelane_b32 v252, s0, 13
	v_add_u32_e32 v109, s0, v108
	v_readlane_b32 s0, v254, 63
	v_or_b32_e32 v2, v2, v70
	v_readlane_b32 s1, v252, 0
	v_lshl_add_u64 v[82:83], s[36:37], 0, v[2:3]
	v_lshl_add_u32 v7, v74, 10, 0
	v_lshl_add_u64 v[86:87], s[0:1], 0, v[2:3]
	v_lshlrev_b32_e32 v2, 2, v9
	v_readlane_b32 s0, v252, 1
	s_mov_b32 s3, s38
	v_add_u32_e32 v99, 0, v8
	v_add_u32_e32 v113, s0, v2
	v_readlane_b32 s0, v252, 2
	v_and_b32_e32 v101, 63, v74
	v_bitop3_b32 v102, v72, 63, v72 bitop3:0x3f
	v_add_u32_e32 v114, s0, v2
	s_add_i32 s0, 0, 0x3000
	v_add_u32_e32 v115, s0, v2
	v_readlane_b32 s0, v252, 3
	v_or_b32_e32 v103, 64, v73
	v_mov_b32_e32 v1, v72
	v_add_u32_e32 v116, s0, v8
	s_mov_b64 s[0:1], 0
	v_writelane_b32 v254, s0, 33
	v_lshl_add_u32 v106, v74, 3, s2
	s_mov_b32 s8, 0
	v_writelane_b32 v254, s1, 34
	s_mov_b64 s[0:1], 0
	v_writelane_b32 v252, s0, 14
	v_sub_u32_e32 v75, 0x1ff, v74
	v_add_u32_e32 v110, 0, v10
	v_writelane_b32 v252, s1, 15
	s_mov_b64 s[0:1], 0
	v_writelane_b32 v252, s0, 16
	v_add_u32_e32 v111, -1, v9
	v_add_u32_e32 v112, 0, v2
	v_writelane_b32 v252, s1, 17
	s_mov_b64 s[0:1], 0
	v_writelane_b32 v252, s0, 18
	s_mov_b64 s[40:41], 0
	v_add_u32_e32 v117, v7, v6
	v_writelane_b32 v252, s1, 19
	s_mov_b64 s[0:1], 0
	v_writelane_b32 v252, s0, 20
	v_writelane_b32 v254, s3, 31
	v_readlane_b32 s17, v253, 21
	v_writelane_b32 v252, s1, 21
	s_mov_b64 s[0:1], 0
	v_writelane_b32 v252, s0, 22
	v_readlane_b32 s18, v253, 22
	v_readlane_b32 s19, v253, 23
	v_writelane_b32 v252, s1, 23
	s_mov_b64 s[0:1], 0
	v_writelane_b32 v252, s0, 24
	v_readlane_b32 s20, v253, 24
	v_readlane_b32 s21, v253, 25
	v_readlane_b32 s22, v253, 26
	v_readlane_b32 s23, v253, 27
	v_readlane_b32 s24, v253, 28
	v_readlane_b32 s25, v253, 29
	v_readlane_b32 s28, v253, 32
	v_readlane_b32 s29, v253, 33
	v_readlane_b32 s30, v253, 34
	v_readlane_b32 s31, v253, 35
	v_writelane_b32 v252, s1, 25
	s_branch .LBB0_1460

; #define LAS __attribute__((address_space(3)))
; DI void snsa_key(const Args& a, int br, int kk, int s, int g, const LAS int* SEL, const int* pt, const float*& kp, const float*& vp, int& dist, bool& valid) {
;     valid = true;
;     if (br == 1) { const int pos = SEL[kk >> 6] * 64 + (kk & 63); dist = PAST - pos; valid = pos <= PAST;
;         if (pos < PAST) { const float* base = INF(a, I_CKV) + ((size_t)pt[pos >> 7] * PAGE + (pos & 127)) * 512; kp = base + 256 + g * 64; vp = base + 384 + g * 64; }
;         else { const float* base = a.out + O_KVS + (size_t)s * 512; kp = base + 256 + g * 64; vp = base + 384 + g * 64; } }
; DI void snsa_unit(const Args& a, LAS unsigned char* lds, int s, int g) {
;     ...
;                 else { const float* kp; const float* vp; snsa_key(a, br, kc, s, g, SEL, pt, kp, vp, dist[u], valid[u]); x[u] = *(const f32x4*)(kp + 4 * c16); if (c16 == 0 && kk < nkeys) VP[kk] = (unsigned long long)(uintptr_t)vp; } }
.LBB0_1468:
	s_andn2_b64 vcc, exec, s[4:5]
	s_cbranch_vccnz .LBB0_1472
	v_ashrrev_i32_e32 v6, 6, v123
	v_lshl_add_u32 v6, v6, 2, 0
	ds_read_b32 v11, v6 offset:62720
	v_mov_b64_e32 v[6:7], s[64:65]
	v_mov_b64_e32 v[8:9], s[62:63]
	s_waitcnt lgkmcnt(0)
	v_lshl_or_b32 v10, v11, 6, v101
	v_cmp_gt_i32_e64 s[20:21], s81, v10
	v_cmp_gt_i32_e32 vcc, s80, v10
	s_and_saveexec_b64 s[4:5], vcc
	s_cbranch_execz .LBB0_1471
	v_ashrrev_i32_e32 v6, 1, v11
	v_lshlrev_b32_e32 v6, 2, v6
	ds_read_b32 v6, v6 offset:62784
	v_lshlrev_b32_e32 v7, 11, v10
	v_and_b32_e32 v70, 0x3f800, v7
	v_readlane_b32 s36, v253, 20
	v_readlane_b32 s44, v253, 28
	v_readlane_b32 s45, v253, 29
	s_lshl_b32 s72, s76, 2
	s_mov_b64 s[24:25], 0x400
	v_readlane_b32 s37, v253, 21
	v_readlane_b32 s38, v253, 22
	v_readlane_b32 s39, v253, 23
	v_readlane_b32 s40, v253, 24
	v_readlane_b32 s41, v253, 25
	v_readlane_b32 s42, v253, 26
	v_readlane_b32 s43, v253, 27
	v_readlane_b32 s46, v253, 30
	v_readlane_b32 s47, v253, 31
	v_readlane_b32 s48, v253, 32
	v_readlane_b32 s49, v253, 33
	v_readlane_b32 s50, v253, 34
	v_readlane_b32 s51, v253, 35
	s_waitcnt lgkmcnt(0)
	v_ashrrev_i32_e32 v7, 31, v6
	v_lshlrev_b64 v[6:7], 18, v[6:7]
	v_lshl_add_u64 v[6:7], s[44:45], 0, v[6:7]
	v_lshl_add_u64 v[6:7], v[6:7], 0, v[70:71]
	v_lshl_add_u64 v[6:7], v[6:7], 0, s[72:73]
	v_lshl_add_u64 v[8:9], v[6:7], 0, s[24:25]
	v_lshl_add_u64 v[6:7], v[6:7], 0, s[84:85]

; #define LAS __attribute__((address_space(3)))
; DI void snsa_key(const Args& a, int br, int kk, int s, int g, const LAS int* SEL, const int* pt, const float*& kp, const float*& vp, int& dist, bool& valid) {
;     valid = true;
;     if (br == 1) { const int pos = SEL[kk >> 6] * 64 + (kk & 63); dist = PAST - pos; valid = pos <= PAST;
;         if (pos < PAST) { const float* base = INF(a, I_CKV) + ((size_t)pt[pos >> 7] * PAGE + (pos & 127)) * 512; kp = base + 256 + g * 64; vp = base + 384 + g * 64; }
;         else { const float* base = a.out + O_KVS + (size_t)s * 512; kp = base + 256 + g * 64; vp = base + 384 + g * 64; } }
; DI void snsa_unit(const Args& a, LAS unsigned char* lds, int s, int g) {
;     ...
;                 else { const float* kp; const float* vp; snsa_key(a, br, kc, s, g, SEL, pt, kp, vp, dist[u], valid[u]); x[u] = *(const f32x4*)(kp + 4 * c16); if (c16 == 0 && kk < nkeys) VP[kk] = (unsigned long long)(uintptr_t)vp; } }
.LBB0_1480:
	s_andn2_b64 vcc, exec, s[4:5]
	s_cbranch_vccnz .LBB0_1484
	v_ashrrev_i32_e32 v6, 6, v46
	v_lshl_add_u32 v6, v6, 2, 0
	ds_read_b32 v7, v6 offset:62720
	v_and_b32_e32 v6, 63, v46
	v_mov_b64_e32 v[48:49], s[64:65]
	v_mov_b64_e32 v[42:43], s[62:63]
	s_waitcnt lgkmcnt(0)
	v_lshl_or_b32 v6, v7, 6, v6
	v_cmp_gt_i32_e64 s[58:59], s81, v6
	v_cmp_gt_i32_e32 vcc, s80, v6
	s_and_saveexec_b64 s[4:5], vcc
	s_cbranch_execz .LBB0_1483
	v_ashrrev_i32_e32 v8, 1, v7
	v_lshlrev_b32_e32 v8, 2, v8
	ds_read_b32 v8, v8 offset:62784
	v_readlane_b32 s36, v253, 20
	v_lshlrev_b32_e32 v7, 11, v6
	v_readlane_b32 s44, v253, 28
	v_readlane_b32 s45, v253, 29
	v_and_b32_e32 v70, 0x3f800, v7
	s_lshl_b32 s72, s76, 2
	v_readlane_b32 s37, v253, 21
	s_mov_b64 s[36:37], 0x400
	v_readlane_b32 s38, v253, 22
	v_readlane_b32 s39, v253, 23
	v_readlane_b32 s40, v253, 24
	v_readlane_b32 s41, v253, 25
	v_readlane_b32 s42, v253, 26
	v_readlane_b32 s43, v253, 27
	v_readlane_b32 s46, v253, 30
	v_readlane_b32 s47, v253, 31
	v_readlane_b32 s48, v253, 32
	v_readlane_b32 s49, v253, 33
	v_readlane_b32 s50, v253, 34
	v_readlane_b32 s51, v253, 35
	s_waitcnt lgkmcnt(0)
	v_ashrrev_i32_e32 v9, 31, v8
	v_lshlrev_b64 v[8:9], 18, v[8:9]
	v_lshl_add_u64 v[8:9], s[44:45], 0, v[8:9]
	v_lshl_add_u64 v[8:9], v[8:9], 0, v[70:71]
	v_lshl_add_u64 v[8:9], v[8:9], 0, s[72:73]
	v_lshl_add_u64 v[42:43], v[8:9], 0, s[36:37]
	v_lshl_add_u64 v[48:49], v[8:9], 0, s[84:85]

; #define LAS __attribute__((address_space(3)))
; DI void snsa_key(const Args& a, int br, int kk, int s, int g, const LAS int* SEL, const int* pt, const float*& kp, const float*& vp, int& dist, bool& valid) {
;     valid = true;
;     if (br == 1) { const int pos = SEL[kk >> 6] * 64 + (kk & 63); dist = PAST - pos; valid = pos <= PAST;
;         if (pos < PAST) { const float* base = INF(a, I_CKV) + ((size_t)pt[pos >> 7] * PAGE + (pos & 127)) * 512; kp = base + 256 + g * 64; vp = base + 384 + g * 64; }
;         else { const float* base = a.out + O_KVS + (size_t)s * 512; kp = base + 256 + g * 64; vp = base + 384 + g * 64; } }
; DI void snsa_unit(const Args& a, LAS unsigned char* lds, int s, int g) {
;     ...
;                 else { const float* kp; const float* vp; snsa_key(a, br, kc, s, g, SEL, pt, kp, vp, dist[u], valid[u]); x[u] = *(const f32x4*)(kp + 4 * c16); if (c16 == 0 && kk < nkeys) VP[kk] = (unsigned long long)(uintptr_t)vp; } }
.LBB0_1492:
	s_andn2_b64 vcc, exec, s[66:67]
	s_cbranch_vccnz .LBB0_1496
	v_ashrrev_i32_e32 v14, 6, v50
	v_lshl_add_u32 v14, v14, 2, 0
	s_waitcnt lgkmcnt(0)
	ds_read_b32 v15, v14 offset:62720
	v_and_b32_e32 v14, 63, v50
	v_mov_b64_e32 v[52:53], s[64:65]
	v_mov_b64_e32 v[46:47], s[62:63]
	s_waitcnt lgkmcnt(0)
	v_lshl_or_b32 v14, v15, 6, v14
	v_cmp_gt_i32_e64 s[4:5], s81, v14
	v_cmp_gt_i32_e32 vcc, s80, v14
	s_and_saveexec_b64 s[66:67], vcc
	s_cbranch_execz .LBB0_1495
	v_ashrrev_i32_e32 v16, 1, v15
	v_lshlrev_b32_e32 v16, 2, v16
	ds_read_b32 v16, v16 offset:62784
	v_readlane_b32 s36, v253, 20
	v_lshlrev_b32_e32 v15, 11, v14
	v_readlane_b32 s44, v253, 28
	v_readlane_b32 s45, v253, 29
	v_and_b32_e32 v70, 0x3f800, v15
	s_lshl_b32 s72, s76, 2
	v_readlane_b32 s37, v253, 21
	s_mov_b64 s[36:37], 0x400
	v_readlane_b32 s38, v253, 22
	v_readlane_b32 s39, v253, 23
	v_readlane_b32 s40, v253, 24
	v_readlane_b32 s41, v253, 25
	v_readlane_b32 s42, v253, 26
	v_readlane_b32 s43, v253, 27
	v_readlane_b32 s46, v253, 30
	v_readlane_b32 s47, v253, 31
	v_readlane_b32 s48, v253, 32
	v_readlane_b32 s49, v253, 33
	v_readlane_b32 s50, v253, 34
	v_readlane_b32 s51, v253, 35
	s_waitcnt lgkmcnt(0)
	v_ashrrev_i32_e32 v17, 31, v16
	v_lshlrev_b64 v[16:17], 18, v[16:17]
	v_lshl_add_u64 v[16:17], s[44:45], 0, v[16:17]
	v_lshl_add_u64 v[16:17], v[16:17], 0, v[70:71]
	v_lshl_add_u64 v[16:17], v[16:17], 0, s[72:73]
	v_lshl_add_u64 v[46:47], v[16:17], 0, s[36:37]
	v_lshl_add_u64 v[52:53], v[16:17], 0, s[84:85]

; #define LAS __attribute__((address_space(3)))
; DI void snsa_key(const Args& a, int br, int kk, int s, int g, const LAS int* SEL, const int* pt, const float*& kp, const float*& vp, int& dist, bool& valid) {
;     valid = true;
;     if (br == 1) { const int pos = SEL[kk >> 6] * 64 + (kk & 63); dist = PAST - pos; valid = pos <= PAST;
;         if (pos < PAST) { const float* base = INF(a, I_CKV) + ((size_t)pt[pos >> 7] * PAGE + (pos & 127)) * 512; kp = base + 256 + g * 64; vp = base + 384 + g * 64; }
;         else { const float* base = a.out + O_KVS + (size_t)s * 512; kp = base + 256 + g * 64; vp = base + 384 + g * 64; } }
; DI void snsa_unit(const Args& a, LAS unsigned char* lds, int s, int g) {
;     ...
;                 else { const float* kp; const float* vp; snsa_key(a, br, kc, s, g, SEL, pt, kp, vp, dist[u], valid[u]); x[u] = *(const f32x4*)(kp + 4 * c16); if (c16 == 0 && kk < nkeys) VP[kk] = (unsigned long long)(uintptr_t)vp; } }
.LBB0_1504:
	s_andn2_b64 vcc, exec, s[68:69]
	s_cbranch_vccnz .LBB0_1508
	v_ashrrev_i32_e32 v6, 6, v54
	v_lshl_add_u32 v6, v6, 2, 0
	ds_read_b32 v7, v6 offset:62720
	v_and_b32_e32 v6, 63, v54
	v_mov_b64_e32 v[56:57], s[64:65]
	v_mov_b64_e32 v[50:51], s[62:63]
	s_waitcnt lgkmcnt(0)
	v_lshl_or_b32 v6, v7, 6, v6
	v_cmp_gt_i32_e64 s[66:67], s81, v6
	v_cmp_gt_i32_e32 vcc, s80, v6
	s_and_saveexec_b64 s[68:69], vcc
	s_cbranch_execz .LBB0_1507
	v_ashrrev_i32_e32 v8, 1, v7
	v_lshlrev_b32_e32 v8, 2, v8
	ds_read_b32 v8, v8 offset:62784
	v_readlane_b32 s36, v253, 20
	v_lshlrev_b32_e32 v7, 11, v6
	v_readlane_b32 s44, v253, 28
	v_readlane_b32 s45, v253, 29
	v_and_b32_e32 v70, 0x3f800, v7
	s_lshl_b32 s72, s76, 2
	v_readlane_b32 s37, v253, 21
	s_mov_b64 s[36:37], 0x400
	v_readlane_b32 s38, v253, 22
	v_readlane_b32 s39, v253, 23
	v_readlane_b32 s40, v253, 24
	v_readlane_b32 s41, v253, 25
	v_readlane_b32 s42, v253, 26
	v_readlane_b32 s43, v253, 27
	v_readlane_b32 s46, v253, 30
	v_readlane_b32 s47, v253, 31
	v_readlane_b32 s48, v253, 32
	v_readlane_b32 s49, v253, 33
	v_readlane_b32 s50, v253, 34
	v_readlane_b32 s51, v253, 35
	s_waitcnt lgkmcnt(0)
	v_ashrrev_i32_e32 v9, 31, v8
	v_lshlrev_b64 v[8:9], 18, v[8:9]
	v_lshl_add_u64 v[8:9], s[44:45], 0, v[8:9]
	v_lshl_add_u64 v[8:9], v[8:9], 0, v[70:71]
	v_lshl_add_u64 v[8:9], v[8:9], 0, s[72:73]
	v_lshl_add_u64 v[50:51], v[8:9], 0, s[36:37]
	v_lshl_add_u64 v[56:57], v[8:9], 0, s[84:85]

; #define LAS __attribute__((address_space(3)))
; DI void snsa_key(const Args& a, int br, int kk, int s, int g, const LAS int* SEL, const int* pt, const float*& kp, const float*& vp, int& dist, bool& valid) {
;     valid = true;
;     if (br == 1) { const int pos = SEL[kk >> 6] * 64 + (kk & 63); dist = PAST - pos; valid = pos <= PAST;
;         if (pos < PAST) { const float* base = INF(a, I_CKV) + ((size_t)pt[pos >> 7] * PAGE + (pos & 127)) * 512; kp = base + 256 + g * 64; vp = base + 384 + g * 64; }
;         else { const float* base = a.out + O_KVS + (size_t)s * 512; kp = base + 256 + g * 64; vp = base + 384 + g * 64; } }
; DI void snsa_unit(const Args& a, LAS unsigned char* lds, int s, int g) {
;     ...
;                 else { const float* kp; const float* vp; snsa_key(a, br, kc, s, g, SEL, pt, kp, vp, dist[u], valid[u]); x[u] = *(const f32x4*)(kp + 4 * c16); if (c16 == 0 && kk < nkeys) VP[kk] = (unsigned long long)(uintptr_t)vp; } }
.LBB0_1516:
	s_andn2_b64 vcc, exec, s[70:71]
	s_cbranch_vccnz .LBB0_1520
	v_ashrrev_i32_e32 v14, 6, v58
	v_lshl_add_u32 v14, v14, 2, 0
	s_waitcnt lgkmcnt(0)
	ds_read_b32 v15, v14 offset:62720
	v_and_b32_e32 v14, 63, v58
	v_mov_b64_e32 v[60:61], s[64:65]
	v_mov_b64_e32 v[54:55], s[62:63]
	s_waitcnt lgkmcnt(0)
	v_lshl_or_b32 v14, v15, 6, v14
	v_cmp_gt_i32_e64 s[68:69], s81, v14
	v_cmp_gt_i32_e32 vcc, s80, v14
	s_and_saveexec_b64 s[70:71], vcc
	s_cbranch_execz .LBB0_1519
	v_ashrrev_i32_e32 v16, 1, v15
	v_lshlrev_b32_e32 v16, 2, v16
	ds_read_b32 v16, v16 offset:62784
	v_readlane_b32 s36, v253, 20
	v_lshlrev_b32_e32 v15, 11, v14
	v_readlane_b32 s44, v253, 28
	v_readlane_b32 s45, v253, 29
	v_and_b32_e32 v70, 0x3f800, v15
	s_lshl_b32 s72, s76, 2
	v_readlane_b32 s37, v253, 21
	s_mov_b64 s[36:37], 0x400
	v_readlane_b32 s38, v253, 22
	v_readlane_b32 s39, v253, 23
	v_readlane_b32 s40, v253, 24
	v_readlane_b32 s41, v253, 25
	v_readlane_b32 s42, v253, 26
	v_readlane_b32 s43, v253, 27
	v_readlane_b32 s46, v253, 30
	v_readlane_b32 s47, v253, 31
	v_readlane_b32 s48, v253, 32
	v_readlane_b32 s49, v253, 33
	v_readlane_b32 s50, v253, 34
	v_readlane_b32 s51, v253, 35
	s_waitcnt lgkmcnt(0)
	v_ashrrev_i32_e32 v17, 31, v16
	v_lshlrev_b64 v[16:17], 18, v[16:17]
	v_lshl_add_u64 v[16:17], s[44:45], 0, v[16:17]
	v_lshl_add_u64 v[16:17], v[16:17], 0, v[70:71]
	v_lshl_add_u64 v[16:17], v[16:17], 0, s[72:73]
	v_lshl_add_u64 v[54:55], v[16:17], 0, s[36:37]
	v_lshl_add_u64 v[60:61], v[16:17], 0, s[84:85]

; #define LAS __attribute__((address_space(3)))
; DI void snsa_key(const Args& a, int br, int kk, int s, int g, const LAS int* SEL, const int* pt, const float*& kp, const float*& vp, int& dist, bool& valid) {
;     valid = true;
;     if (br == 1) { const int pos = SEL[kk >> 6] * 64 + (kk & 63); dist = PAST - pos; valid = pos <= PAST;
;         if (pos < PAST) { const float* base = INF(a, I_CKV) + ((size_t)pt[pos >> 7] * PAGE + (pos & 127)) * 512; kp = base + 256 + g * 64; vp = base + 384 + g * 64; }
;         else { const float* base = a.out + O_KVS + (size_t)s * 512; kp = base + 256 + g * 64; vp = base + 384 + g * 64; } }
; DI void snsa_unit(const Args& a, LAS unsigned char* lds, int s, int g) {
;     ...
;                 else { const float* kp; const float* vp; snsa_key(a, br, kc, s, g, SEL, pt, kp, vp, dist[u], valid[u]); x[u] = *(const f32x4*)(kp + 4 * c16); if (c16 == 0 && kk < nkeys) VP[kk] = (unsigned long long)(uintptr_t)vp; } }
.LBB0_1528:
	s_andn2_b64 vcc, exec, s[78:79]
	s_cbranch_vccnz .LBB0_1532
	v_ashrrev_i32_e32 v6, 6, v62
	v_lshl_add_u32 v6, v6, 2, 0
	ds_read_b32 v7, v6 offset:62720
	v_and_b32_e32 v6, 63, v62
	v_mov_b64_e32 v[64:65], s[64:65]
	v_mov_b64_e32 v[58:59], s[62:63]
	s_waitcnt lgkmcnt(0)
	v_lshl_or_b32 v6, v7, 6, v6
	v_cmp_gt_i32_e64 s[70:71], s81, v6
	v_cmp_gt_i32_e32 vcc, s80, v6
	s_and_saveexec_b64 s[78:79], vcc
	s_cbranch_execz .LBB0_1531
	v_ashrrev_i32_e32 v8, 1, v7
	v_lshlrev_b32_e32 v8, 2, v8
	ds_read_b32 v8, v8 offset:62784
	v_readlane_b32 s36, v253, 20
	v_lshlrev_b32_e32 v7, 11, v6
	v_readlane_b32 s44, v253, 28
	v_readlane_b32 s45, v253, 29
	v_and_b32_e32 v70, 0x3f800, v7
	s_lshl_b32 s72, s76, 2
	v_readlane_b32 s37, v253, 21
	s_mov_b64 s[36:37], 0x400
	v_readlane_b32 s38, v253, 22
	v_readlane_b32 s39, v253, 23
	v_readlane_b32 s40, v253, 24
	v_readlane_b32 s41, v253, 25
	v_readlane_b32 s42, v253, 26
	v_readlane_b32 s43, v253, 27
	v_readlane_b32 s46, v253, 30
	v_readlane_b32 s47, v253, 31
	v_readlane_b32 s48, v253, 32
	v_readlane_b32 s49, v253, 33
	v_readlane_b32 s50, v253, 34
	v_readlane_b32 s51, v253, 35
	s_waitcnt lgkmcnt(0)
	v_ashrrev_i32_e32 v9, 31, v8
	v_lshlrev_b64 v[8:9], 18, v[8:9]
	v_lshl_add_u64 v[8:9], s[44:45], 0, v[8:9]
	v_lshl_add_u64 v[8:9], v[8:9], 0, v[70:71]
	v_lshl_add_u64 v[8:9], v[8:9], 0, s[72:73]
	v_lshl_add_u64 v[58:59], v[8:9], 0, s[36:37]
	v_lshl_add_u64 v[64:65], v[8:9], 0, s[84:85]

; #define LAS __attribute__((address_space(3)))
; DI void snsa_key(const Args& a, int br, int kk, int s, int g, const LAS int* SEL, const int* pt, const float*& kp, const float*& vp, int& dist, bool& valid) {
;     valid = true;
;     if (br == 1) { const int pos = SEL[kk >> 6] * 64 + (kk & 63); dist = PAST - pos; valid = pos <= PAST;
;         if (pos < PAST) { const float* base = INF(a, I_CKV) + ((size_t)pt[pos >> 7] * PAGE + (pos & 127)) * 512; kp = base + 256 + g * 64; vp = base + 384 + g * 64; }
;         else { const float* base = a.out + O_KVS + (size_t)s * 512; kp = base + 256 + g * 64; vp = base + 384 + g * 64; } }
; DI void snsa_unit(const Args& a, LAS unsigned char* lds, int s, int g) {
;     ...
;                 else { const float* kp; const float* vp; snsa_key(a, br, kc, s, g, SEL, pt, kp, vp, dist[u], valid[u]); x[u] = *(const f32x4*)(kp + 4 * c16); if (c16 == 0 && kk < nkeys) VP[kk] = (unsigned long long)(uintptr_t)vp; } }
.LBB0_1540:
	s_andn2_b64 vcc, exec, s[82:83]
	s_cbranch_vccnz .LBB0_1544
	v_ashrrev_i32_e32 v14, 6, v66
	v_lshl_add_u32 v14, v14, 2, 0
	s_waitcnt lgkmcnt(0)
	ds_read_b32 v15, v14 offset:62720
	v_and_b32_e32 v14, 63, v66
	v_mov_b64_e32 v[68:69], s[64:65]
	v_mov_b64_e32 v[62:63], s[62:63]
	s_waitcnt lgkmcnt(0)
	v_lshl_or_b32 v14, v15, 6, v14
	v_cmp_gt_i32_e64 s[78:79], s81, v14
	v_cmp_gt_i32_e32 vcc, s80, v14
	s_and_saveexec_b64 s[82:83], vcc
	s_cbranch_execz .LBB0_1543
	v_ashrrev_i32_e32 v16, 1, v15
	v_lshlrev_b32_e32 v16, 2, v16
	ds_read_b32 v16, v16 offset:62784
	v_readlane_b32 s36, v253, 20
	v_lshlrev_b32_e32 v15, 11, v14
	v_readlane_b32 s44, v253, 28
	v_readlane_b32 s45, v253, 29
	v_and_b32_e32 v70, 0x3f800, v15
	s_lshl_b32 s72, s76, 2
	v_readlane_b32 s37, v253, 21
	s_mov_b64 s[36:37], 0x400
	v_readlane_b32 s38, v253, 22
	v_readlane_b32 s39, v253, 23
	v_readlane_b32 s40, v253, 24
	v_readlane_b32 s41, v253, 25
	v_readlane_b32 s42, v253, 26
	v_readlane_b32 s43, v253, 27
	v_readlane_b32 s46, v253, 30
	v_readlane_b32 s47, v253, 31
	v_readlane_b32 s48, v253, 32
	v_readlane_b32 s49, v253, 33
	v_readlane_b32 s50, v253, 34
	v_readlane_b32 s51, v253, 35
	s_waitcnt lgkmcnt(0)
	v_ashrrev_i32_e32 v17, 31, v16
	v_lshlrev_b64 v[16:17], 18, v[16:17]
	v_lshl_add_u64 v[16:17], s[44:45], 0, v[16:17]
	v_lshl_add_u64 v[16:17], v[16:17], 0, v[70:71]
	v_lshl_add_u64 v[16:17], v[16:17], 0, s[72:73]
	v_lshl_add_u64 v[62:63], v[16:17], 0, s[36:37]
	v_lshl_add_u64 v[68:69], v[16:17], 0, s[84:85]

; #define LAS __attribute__((address_space(3)))
; DI void snsa_key(const Args& a, int br, int kk, int s, int g, const LAS int* SEL, const int* pt, const float*& kp, const float*& vp, int& dist, bool& valid) {
;     valid = true;
;     if (br == 1) { const int pos = SEL[kk >> 6] * 64 + (kk & 63); dist = PAST - pos; valid = pos <= PAST;
;         if (pos < PAST) { const float* base = INF(a, I_CKV) + ((size_t)pt[pos >> 7] * PAGE + (pos & 127)) * 512; kp = base + 256 + g * 64; vp = base + 384 + g * 64; }
;         else { const float* base = a.out + O_KVS + (size_t)s * 512; kp = base + 256 + g * 64; vp = base + 384 + g * 64; } }
; DI void snsa_unit(const Args& a, LAS unsigned char* lds, int s, int g) {
;     ...
;                 else { const float* kp; const float* vp; snsa_key(a, br, kc, s, g, SEL, pt, kp, vp, dist[u], valid[u]); x[u] = *(const f32x4*)(kp + 4 * c16); if (c16 == 0 && kk < nkeys) VP[kk] = (unsigned long long)(uintptr_t)vp; } }
.LBB0_1552:
	s_andn2_b64 vcc, exec, s[24:25]
	s_cbranch_vccnz .LBB0_1556
	v_ashrrev_i32_e32 v6, 6, v92
	v_lshl_add_u32 v6, v6, 2, 0
	ds_read_b32 v7, v6 offset:62720
	v_and_b32_e32 v6, 63, v92
	v_mov_b64_e32 v[94:95], s[64:65]
	v_mov_b64_e32 v[66:67], s[62:63]
	s_waitcnt lgkmcnt(0)
	v_lshl_or_b32 v6, v7, 6, v6
	v_cmp_gt_i32_e64 s[26:27], s81, v6
	v_cmp_gt_i32_e32 vcc, s80, v6
	s_and_saveexec_b64 s[24:25], vcc
	s_cbranch_execz .LBB0_1555
	v_ashrrev_i32_e32 v8, 1, v7
	v_lshlrev_b32_e32 v8, 2, v8
	ds_read_b32 v8, v8 offset:62784
	v_readlane_b32 s80, v253, 20
	v_lshlrev_b32_e32 v7, 11, v6
	v_readlane_b32 s88, v253, 28
	v_readlane_b32 s89, v253, 29
	v_and_b32_e32 v70, 0x3f800, v7
	s_lshl_b32 s72, s76, 2
	v_readlane_b32 s84, v253, 24
	v_readlane_b32 s85, v253, 25
	v_readlane_b32 s81, v253, 21
	v_readlane_b32 s86, v253, 26
	v_readlane_b32 s87, v253, 27
	v_readlane_b32 s90, v253, 30
	v_readlane_b32 s91, v253, 31
	v_readlane_b32 s92, v253, 32
	v_readlane_b32 s93, v253, 33
	v_readlane_b32 s94, v253, 34
	v_readlane_b32 s95, v253, 35
	s_mov_b64 s[84:85], 0x600
	s_mov_b64 s[36:37], 0x400
	s_movk_i32 s95, 0x315
	s_movk_i32 s94, 0x260
	s_movk_i32 s93, 0x1d5
	s_movk_i32 s92, 0x16a
	s_movk_i32 s91, 0x117
	s_movk_i32 s90, 0xd7
	s_movk_i32 s87, 0x62
	s_movk_i32 s86, 0x4c
	s_movk_i32 s81, 0x4001
	s_movk_i32 s80, 0x4000
	v_readlane_b32 s82, v253, 22
	v_readlane_b32 s83, v253, 23
	s_waitcnt lgkmcnt(0)
	v_ashrrev_i32_e32 v9, 31, v8
	v_lshlrev_b64 v[8:9], 18, v[8:9]
	v_lshl_add_u64 v[8:9], s[88:89], 0, v[8:9]
	v_lshl_add_u64 v[8:9], v[8:9], 0, v[70:71]
	v_lshl_add_u64 v[8:9], v[8:9], 0, s[72:73]
	s_movk_i32 s89, 0xa5
	s_movk_i32 s88, 0x7f
	v_lshl_add_u64 v[66:67], v[8:9], 0, s[36:37]
	v_lshl_add_u64 v[94:95], v[8:9], 0, s[84:85]

; DI unsigned pk2(float lo, float hi) { f32x2 v = {lo, hi}; bf16x2_t b = __builtin_convertvector(v, bf16x2_t); return __builtin_bit_cast(unsigned, b); }
; DI void nsa_unit(const Args& a, LAS unsigned char* lds, int b, int g, int jb) {
;     ...
;         {
;             const float lt = l + __shfl_xor(l, 32); const float sc = gate_s / fmaxf(lt, 1e-30f);
;             bf16_t* op = (bf16_t*)(ws + WS_OAHB) + row * 1024 + (g * 4 + hh) * 64;
; #pragma unroll
;             for (int db = 0; db < 2; ++db)
; #pragma unroll
;                 for (int rg = 0; rg < 4; ++rg) { float o[4];
; #pragma unroll
;                     for (int i = 0; i < 4; ++i) o[i] = oscr[(db * 16 + 4 * rg + i) * 64] + O[db][4 * rg + i] * sc;
;                     u32x2 w; w.x = pk2(o[0], o[1]); w.y = pk2(o[2], o[3]); *(u32x2*)(op + 32 * db + 8 * rg + 4 * h2) = w; }
;         }
.LBB0_2077:
	s_mov_b64 s[0:1], exec
	v_readlane_b32 s2, v254, 43
	v_readlane_b32 s3, v254, 44
	s_and_b64 s[2:3], s[0:1], s[2:3]
	s_mov_b64 exec, s[2:3]
	s_cbranch_execz .Lnu_skip
	v_readlane_b32 s4, v254, 45
	v_readlane_b32 s5, v254, 46
	v_mov_b32_e32 v4, 1
	s_nop 4
	global_atomic_add v4, v2, v4, s[4:5] offset:256 sc0
.Lnu_skip:
	s_mov_b64 exec, s[0:1]
	global_load_dword v190, v[152:153], off
	global_load_dword v191, v[152:153], off offset:256
	global_load_dword v192, v[152:153], off offset:512
	global_load_dword v193, v[152:153], off offset:768
	global_load_dword v194, v[152:153], off offset:1024
	global_load_dword v195, v[152:153], off offset:1280
	global_load_dword v196, v[152:153], off offset:1536
	global_load_dword v197, v[152:153], off offset:1792
	global_load_dword v198, v[152:153], off offset:2048
	global_load_dword v199, v[152:153], off offset:2304
	global_load_dword v200, v[152:153], off offset:2560
	global_load_dword v201, v[152:153], off offset:2816
	global_load_dword v202, v[152:153], off offset:3072
	global_load_dword v203, v[152:153], off offset:3328
	global_load_dword v204, v[152:153], off offset:3584
	global_load_dword v205, v[152:153], off offset:3840
	global_load_dword v206, v[186:187], off
	global_load_dword v207, v[188:189], off
	global_load_dword v208, v[182:183], off
	global_load_dword v209, v[184:185], off
	global_load_dword v210, v[178:179], off
	global_load_dword v211, v[180:181], off
	global_load_dword v212, v[174:175], off
	global_load_dword v213, v[176:177], off
	global_load_dword v236, v[168:169], off
	global_load_dword v237, v[170:171], off
	global_load_dword v238, v[164:165], off
	global_load_dword v239, v[166:167], off
	global_load_dword v240, v[160:161], off
	global_load_dword v241, v[162:163], off
	global_load_dword v242, v[154:155], off
	global_load_dword v243, v[156:157], off
	ds_bpermute_b32 v3, v151, v231
	v_lshlrev_b64 v[8:9], 11, v[148:149]
	v_readlane_b32 s0, v254, 11
	v_readlane_b32 s1, v254, 12
	s_lshl_b32 s0, s24, 1
	s_waitcnt lgkmcnt(0)
	v_add_f32_e32 v3, v231, v3
	v_lshl_add_u64 v[8:9], s[62:63], 0, v[8:9]
	v_max_f32_e32 v3, 0xda24260, v3
	s_mov_b32 s77, s1
	v_lshl_add_u64 v[8:9], v[8:9], 0, s[0:1]
	v_div_scale_f32 v12, s[0:1], v3, v3, v143
	v_rcp_f32_e32 v13, v12
	v_lshlrev_b32_e32 v10, 1, v222
	v_mov_b32_e32 v11, v2
	v_lshl_add_u64 v[8:9], v[8:9], 0, v[10:11]
	v_fma_f32 v11, -v12, v13, 1.0
	v_div_scale_f32 v10, vcc, v143, v3, v143
	v_fmac_f32_e32 v13, v11, v13
	v_mul_f32_e32 v11, v10, v13
	v_fma_f32 v14, -v12, v11, v10
	v_fmac_f32_e32 v11, v14, v13
	v_fma_f32 v10, -v12, v11, v10
	v_div_fmas_f32 v10, v10, v13, v11
	v_div_fixup_f32 v10, v10, v3, v143
	v_readlane_b32 s73, v254, 7
	v_readlane_b32 s2, v254, 13
	v_readlane_b32 s3, v254, 14
	v_readlane_b32 s4, v254, 15
	v_readlane_b32 s5, v254, 16
	v_readlane_b32 s6, v254, 17
	v_readlane_b32 s7, v254, 18
	v_readlane_b32 s8, v254, 19
	v_readlane_b32 s9, v254, 20
	v_readlane_b32 s10, v254, 21
	v_readlane_b32 s11, v254, 22
	v_readlane_b32 s12, v254, 23
	v_readlane_b32 s13, v254, 24
	v_readlane_b32 s14, v254, 25
	v_readlane_b32 s15, v254, 26
	s_waitcnt vmcnt(28)
	v_pk_fma_f32 v[190:191], v[18:19], v[10:11], v[190:191] op_sel_hi:[1,0,1]
	v_pk_fma_f32 v[192:193], v[20:21], v[10:11], v[192:193] op_sel_hi:[1,0,1]
	s_nop 0
	v_cvt_pk_bf16_f32 v190, v190, v191
	v_cvt_pk_bf16_f32 v191, v192, v193
	s_waitcnt vmcnt(24)
	v_pk_fma_f32 v[194:195], v[22:23], v[10:11], v[194:195] op_sel_hi:[1,0,1]
	v_pk_fma_f32 v[196:197], v[24:25], v[10:11], v[196:197] op_sel_hi:[1,0,1]
	s_nop 0
	v_cvt_pk_bf16_f32 v194, v194, v195
	v_cvt_pk_bf16_f32 v195, v196, v197
	s_waitcnt vmcnt(20)
	v_pk_fma_f32 v[198:199], v[26:27], v[10:11], v[198:199] op_sel_hi:[1,0,1]
	v_pk_fma_f32 v[200:201], v[28:29], v[10:11], v[200:201] op_sel_hi:[1,0,1]
	s_nop 0
	v_cvt_pk_bf16_f32 v198, v198, v199
	v_cvt_pk_bf16_f32 v199, v200, v201
	s_waitcnt vmcnt(16)
	v_pk_fma_f32 v[202:203], v[30:31], v[10:11], v[202:203] op_sel_hi:[1,0,1]
	v_pk_fma_f32 v[204:205], v[32:33], v[10:11], v[204:205] op_sel_hi:[1,0,1]
	s_nop 0
	v_cvt_pk_bf16_f32 v202, v202, v203
	v_cvt_pk_bf16_f32 v203, v204, v205
	s_waitcnt vmcnt(12)
	v_pk_fma_f32 v[206:207], v[34:35], v[10:11], v[206:207] op_sel_hi:[1,0,1]
	v_pk_fma_f32 v[208:209], v[36:37], v[10:11], v[208:209] op_sel_hi:[1,0,1]
	s_nop 0
	v_cvt_pk_bf16_f32 v206, v206, v207
	v_cvt_pk_bf16_f32 v207, v208, v209
	s_waitcnt vmcnt(8)
	v_pk_fma_f32 v[210:211], v[38:39], v[10:11], v[210:211] op_sel_hi:[1,0,1]
	v_pk_fma_f32 v[212:213], v[40:41], v[10:11], v[212:213] op_sel_hi:[1,0,1]
	s_nop 0
	v_cvt_pk_bf16_f32 v210, v210, v211
	v_cvt_pk_bf16_f32 v211, v212, v213
	s_waitcnt vmcnt(4)
	v_pk_fma_f32 v[236:237], v[42:43], v[10:11], v[236:237] op_sel_hi:[1,0,1]
	v_pk_fma_f32 v[238:239], v[44:45], v[10:11], v[238:239] op_sel_hi:[1,0,1]
	s_nop 0
	v_cvt_pk_bf16_f32 v236, v236, v237
	v_cvt_pk_bf16_f32 v237, v238, v239
	s_waitcnt vmcnt(0)
	v_pk_fma_f32 v[240:241], v[46:47], v[10:11], v[240:241] op_sel_hi:[1,0,1]
	v_pk_fma_f32 v[242:243], v[48:49], v[10:11], v[242:243] op_sel_hi:[1,0,1]
	s_nop 0
	v_cvt_pk_bf16_f32 v240, v240, v241
	v_cvt_pk_bf16_f32 v241, v242, v243
	global_store_dwordx2 v[8:9], v[190:191], off
	global_store_dwordx2 v[8:9], v[194:195], off offset:16
	global_store_dwordx2 v[8:9], v[198:199], off offset:32
	global_store_dwordx2 v[8:9], v[202:203], off offset:48
	global_store_dwordx2 v[8:9], v[206:207], off offset:64
	global_store_dwordx2 v[8:9], v[210:211], off offset:80
	global_store_dwordx2 v[8:9], v[236:237], off offset:96
	global_store_dwordx2 v[8:9], v[240:241], off offset:112
	s_barrier
	s_mov_b64 s[0:1], exec
	v_readlane_b32 s2, v254, 43
	v_readlane_b32 s3, v254, 44
	s_and_b64 s[2:3], s[0:1], s[2:3]
	s_mov_b64 exec, s[2:3]
	s_cbranch_execz .LBB0_1750
	s_mov_b64 s[4:5], exec
	v_mbcnt_lo_u32_b32 v3, s4, 0
	v_mbcnt_hi_u32_b32 v3, s5, v3
	v_cmp_eq_u32_e32 vcc, 0, v3
	s_and_saveexec_b64 s[2:3], vcc
	s_cbranch_execz .LBB0_1749
	s_bcnt1_i32_b64 s4, s[4:5]
	v_readlane_b32 s4, v254, 45
	v_readlane_b32 s5, v254, 46
	s_nop 4
	s_branch .LBB0_1749
